# out-projection K-loop: the four loop-invariant LDS read base addresses computed once per unit (spare v250-v253) instead of four VALU per iteration
# baseline (speedup 1.0000x reference)
.LBB0_639:
	v_add_u32_e32 v250, s71, v139
	v_add_u32_e32 v251, s72, v139
	v_add_u32_e32 v252, s79, v139
	v_add_u32_e32 v253, 0x1c000, v139
	s_mov_b64 s[34:35], s[8:9]
	s_add_u32 s83, s34, 0x100
	s_addc_u32 s84, s35, 0
	v_add_co_u32_e64 v56, s[26:27], s80, 1
	s_and_b64 s[8:9], s[26:27], exec
	s_cselect_b32 s10, s4, s69
	s_cselect_b32 s82, s66, 0
	s_cmp_gt_i32 s80, 0
	s_cselect_b64 s[20:21], -1, 0
	s_ashr_i32 s11, s10, 31
	s_lshl_b64 s[8:9], s[10:11], 21
	s_add_u32 s3, s56, s8
	s_addc_u32 s8, s57, s9
	s_lshl_b32 s9, s82, 1
	s_add_u32 s24, s3, s9
	s_addc_u32 s25, s8, 0
	s_add_u32 s8, s42, s9
	s_addc_u32 s9, s43, 0
	s_cmp_lt_i32 s80, 1
	s_cselect_b64 s[28:29], -1, 0
	s_and_b64 s[36:37], s[28:29], exec
	s_cselect_b32 s11, s25, s23
	s_cselect_b32 s85, s24, s22
	s_cselect_b32 s86, s9, s35
	s_cselect_b32 s87, s8, s34
	s_lshl_b32 s3, s49, 7
	s_addk_i32 s3, 0xfc00
	v_readfirstlane_b32 s81, v56
	v_lshl_add_u64 v[58:59], s[22:23], 0, v[142:143]
	v_lshl_add_u64 v[146:147], s[22:23], 0, v[144:145]
	s_add_u32 s88, s3, 0x300
	s_mov_b64 s[34:35], 0
	s_mov_b32 s89, 0
	s_add_i32 s89, s89, 2
	s_add_u32 s3, s22, s34
	ds_read_b128 v[150:153], v250
	ds_read_b128 v[154:157], v250 offset:1024
	ds_read_b128 v[158:161], v250 offset:2048
	ds_read_b128 v[162:165], v250 offset:3072
	s_addc_u32 s36, s23, s35
	s_add_u32 s3, s3, 0x100
	s_addc_u32 s36, s36, 0
	s_add_u32 s90, s83, s34
	s_addc_u32 s37, s84, s35
	s_cmp_eq_u32 s88, s34
	s_cselect_b32 s39, s11, s36
	s_cselect_b32 s38, s85, s3
	s_cselect_b32 s37, s86, s37
	s_cselect_b32 s36, s87, s90
	s_mov_b32 m0, s73
	v_lshl_add_u64 v[174:175], v[58:59], 0, s[34:35]
	ds_read_b128 v[166:169], v133
	ds_read_b128 v[170:173], v133 offset:1024
	ds_read_b128 v[182:185], v133 offset:2048
	ds_read_b128 v[186:189], v133 offset:3072
	ds_read_b128 v[190:193], v133 offset:4096
	ds_read_b128 v[194:197], v133 offset:5120
	ds_read_b128 v[198:201], v133 offset:6144
	ds_read_b128 v[202:205], v133 offset:7168
	global_load_lds_dwordx4 v[174:175], off
	s_mov_b32 m0, s74
	v_lshl_add_u64 v[174:175], v[146:147], 0, s[34:35]
	global_load_lds_dwordx4 v[174:175], off
	s_waitcnt lgkmcnt(8)
	s_barrier
	s_waitcnt lgkmcnt(0)
	v_mfma_f32_16x16x32_bf16 v[128:131], v[150:153], v[166:169], 0
	v_mfma_f32_16x16x32_bf16 v[124:127], v[158:161], v[166:169], 0
	v_mfma_f32_16x16x32_bf16 v[112:115], v[150:153], v[182:185], 0
	v_mfma_f32_16x16x32_bf16 v[108:111], v[158:161], v[182:185], 0
	v_mfma_f32_16x16x32_bf16 v[96:99], v[150:153], v[190:193], 0
	v_mfma_f32_16x16x32_bf16 v[92:95], v[158:161], v[190:193], 0
	v_mfma_f32_16x16x32_bf16 v[80:83], v[150:153], v[198:201], 0
	v_mfma_f32_16x16x32_bf16 v[76:79], v[158:161], v[198:201], 0
	v_mfma_f32_16x16x32_bf16 v[128:131], v[154:157], v[170:173], v[128:131]
	v_mfma_f32_16x16x32_bf16 v[124:127], v[162:165], v[170:173], v[124:127]
	v_mfma_f32_16x16x32_bf16 v[112:115], v[154:157], v[186:189], v[112:115]
	v_mfma_f32_16x16x32_bf16 v[108:111], v[162:165], v[186:189], v[108:111]
	v_mfma_f32_16x16x32_bf16 v[96:99], v[154:157], v[194:197], v[96:99]
	v_mfma_f32_16x16x32_bf16 v[92:95], v[162:165], v[194:197], v[92:95]
	v_mfma_f32_16x16x32_bf16 v[80:83], v[154:157], v[202:205], v[80:83]
	v_mfma_f32_16x16x32_bf16 v[76:79], v[162:165], v[202:205], v[76:79]
	s_barrier
	s_mov_b32 m0, s75
	v_lshl_add_u64 v[174:175], s[36:37], 0, v[134:135]
	ds_read_b128 v[206:209], v251
	ds_read_b128 v[214:217], v251 offset:1024
	ds_read_b128 v[218:221], v251 offset:2048
	ds_read_b128 v[222:225], v251 offset:3072
	global_load_lds_dwordx4 v[174:175], off
	s_mov_b32 m0, s76
	v_lshl_add_u64 v[226:227], s[36:37], 0, v[136:137]
	global_load_lds_dwordx4 v[226:227], off
	s_barrier
	s_waitcnt lgkmcnt(0)
	v_mfma_f32_16x16x32_bf16 v[120:123], v[206:209], v[166:169], 0
	v_mfma_f32_16x16x32_bf16 v[116:119], v[218:221], v[166:169], 0
	v_mfma_f32_16x16x32_bf16 v[104:107], v[206:209], v[182:185], 0
	v_mfma_f32_16x16x32_bf16 v[100:103], v[218:221], v[182:185], 0
	v_mfma_f32_16x16x32_bf16 v[88:91], v[206:209], v[190:193], 0
	v_mfma_f32_16x16x32_bf16 v[84:87], v[218:221], v[190:193], 0
	v_mfma_f32_16x16x32_bf16 v[72:75], v[206:209], v[198:201], 0
	v_mfma_f32_16x16x32_bf16 v[68:71], v[218:221], v[198:201], 0
	v_mfma_f32_16x16x32_bf16 v[120:123], v[214:217], v[170:173], v[120:123]
	v_mfma_f32_16x16x32_bf16 v[116:119], v[222:225], v[170:173], v[116:119]
	v_mfma_f32_16x16x32_bf16 v[104:107], v[214:217], v[186:189], v[104:107]
	v_mfma_f32_16x16x32_bf16 v[100:103], v[222:225], v[186:189], v[100:103]
	v_mfma_f32_16x16x32_bf16 v[88:91], v[214:217], v[194:197], v[88:91]
	v_mfma_f32_16x16x32_bf16 v[84:87], v[222:225], v[194:197], v[84:87]
	v_mfma_f32_16x16x32_bf16 v[72:75], v[214:217], v[202:205], v[72:75]
	v_mfma_f32_16x16x32_bf16 v[68:71], v[222:225], v[202:205], v[68:71]
	s_mov_b32 m0, s44
	v_lshl_add_u64 v[228:229], s[38:39], 0, v[134:135]
	s_barrier
	ds_read_b128 v[166:169], v133 offset:16384
	ds_read_b128 v[170:173], v133 offset:17408
	ds_read_b128 v[182:185], v133 offset:18432
	ds_read_b128 v[186:189], v133 offset:19456
	ds_read_b128 v[190:193], v133 offset:20480
	ds_read_b128 v[194:197], v133 offset:21504
	ds_read_b128 v[198:201], v133 offset:22528
	ds_read_b128 v[202:205], v133 offset:23552
	global_load_lds_dwordx4 v[228:229], off
	s_mov_b32 m0, s45
	v_lshl_add_u64 v[230:231], s[38:39], 0, v[136:137]
	global_load_lds_dwordx4 v[230:231], off
	s_barrier
	s_waitcnt lgkmcnt(0)
	v_mfma_f32_16x16x32_bf16 v[64:67], v[150:153], v[166:169], 0
	v_mfma_f32_16x16x32_bf16 v[60:63], v[158:161], v[166:169], 0
	v_mfma_f32_16x16x32_bf16 v[44:47], v[150:153], v[182:185], 0
	v_mfma_f32_16x16x32_bf16 v[40:43], v[158:161], v[182:185], 0
	v_mfma_f32_16x16x32_bf16 v[28:31], v[150:153], v[190:193], 0
	v_mfma_f32_16x16x32_bf16 v[24:27], v[158:161], v[190:193], 0
	v_mfma_f32_16x16x32_bf16 v[12:15], v[150:153], v[198:201], 0
	v_mfma_f32_16x16x32_bf16 v[8:11], v[158:161], v[198:201], 0
	v_mfma_f32_16x16x32_bf16 v[64:67], v[154:157], v[170:173], v[64:67]
	v_mfma_f32_16x16x32_bf16 v[60:63], v[162:165], v[170:173], v[60:63]
	v_mfma_f32_16x16x32_bf16 v[44:47], v[154:157], v[186:189], v[44:47]
	v_mfma_f32_16x16x32_bf16 v[40:43], v[162:165], v[186:189], v[40:43]
	v_mfma_f32_16x16x32_bf16 v[28:31], v[154:157], v[194:197], v[28:31]
	v_mfma_f32_16x16x32_bf16 v[24:27], v[162:165], v[194:197], v[24:27]
	v_mfma_f32_16x16x32_bf16 v[12:15], v[154:157], v[202:205], v[12:15]
	v_mfma_f32_16x16x32_bf16 v[8:11], v[162:165], v[202:205], v[8:11]
	s_barrier
	s_add_u32 s90, s36, 0x100000
	s_addc_u32 s91, s37, 0
	s_mov_b32 m0, s77
	v_lshl_add_u64 v[150:151], s[90:91], 0, v[134:135]
	global_load_lds_dwordx4 v[150:151], off
	s_mov_b32 m0, s78
	v_lshl_add_u64 v[150:151], s[90:91], 0, v[136:137]
	global_load_lds_dwordx4 v[150:151], off
	s_waitcnt vmcnt(6)
	s_barrier
	v_mfma_f32_16x16x32_bf16 v[52:55], v[206:209], v[166:169], 0
	v_mfma_f32_16x16x32_bf16 v[48:51], v[218:221], v[166:169], 0
	v_mfma_f32_16x16x32_bf16 v[36:39], v[206:209], v[182:185], 0
	v_mfma_f32_16x16x32_bf16 v[32:35], v[218:221], v[182:185], 0
	v_mfma_f32_16x16x32_bf16 v[20:23], v[206:209], v[190:193], 0
	v_mfma_f32_16x16x32_bf16 v[16:19], v[218:221], v[190:193], 0
	v_mfma_f32_16x16x32_bf16 v[4:7], v[206:209], v[198:201], 0
	v_mfma_f32_16x16x32_bf16 v[0:3], v[218:221], v[198:201], 0
	v_mfma_f32_16x16x32_bf16 v[52:55], v[214:217], v[170:173], v[52:55]
	v_mfma_f32_16x16x32_bf16 v[48:51], v[222:225], v[170:173], v[48:51]
	v_mfma_f32_16x16x32_bf16 v[36:39], v[214:217], v[186:189], v[36:39]
	v_mfma_f32_16x16x32_bf16 v[32:35], v[222:225], v[186:189], v[32:35]
	v_mfma_f32_16x16x32_bf16 v[20:23], v[214:217], v[194:197], v[20:23]
	v_mfma_f32_16x16x32_bf16 v[16:19], v[222:225], v[194:197], v[16:19]
	v_mfma_f32_16x16x32_bf16 v[4:7], v[214:217], v[202:205], v[4:7]
	v_mfma_f32_16x16x32_bf16 v[0:3], v[222:225], v[202:205], v[0:3]
	s_barrier
	ds_read_b128 v[150:153], v252
	ds_read_b128 v[154:157], v252 offset:1024
	ds_read_b128 v[158:161], v252 offset:2048
	ds_read_b128 v[162:165], v252 offset:3072
	s_add_u32 s38, s38, 0x100000
	s_addc_u32 s39, s39, 0
	s_mov_b32 m0, s46
	v_lshl_add_u64 v[206:207], s[38:39], 0, v[134:135]
	ds_read_b128 v[166:169], v133 offset:32768
	ds_read_b128 v[170:173], v133 offset:33792
	ds_read_b128 v[182:185], v133 offset:34816
	ds_read_b128 v[186:189], v133 offset:35840
	ds_read_b128 v[190:193], v133 offset:36864
	ds_read_b128 v[194:197], v133 offset:37888
	ds_read_b128 v[198:201], v133 offset:38912
	ds_read_b128 v[202:205], v133 offset:39936
	global_load_lds_dwordx4 v[206:207], off
	s_mov_b32 m0, s47
	v_lshl_add_u64 v[206:207], s[38:39], 0, v[136:137]
	global_load_lds_dwordx4 v[206:207], off
	s_waitcnt lgkmcnt(8)
	s_barrier
	s_waitcnt lgkmcnt(0)
	v_mfma_f32_16x16x32_bf16 v[128:131], v[150:153], v[166:169], v[128:131]
	v_mfma_f32_16x16x32_bf16 v[124:127], v[158:161], v[166:169], v[124:127]
	v_mfma_f32_16x16x32_bf16 v[112:115], v[150:153], v[182:185], v[112:115]
	v_mfma_f32_16x16x32_bf16 v[108:111], v[158:161], v[182:185], v[108:111]
	v_mfma_f32_16x16x32_bf16 v[96:99], v[150:153], v[190:193], v[96:99]
	v_mfma_f32_16x16x32_bf16 v[92:95], v[158:161], v[190:193], v[92:95]
	v_mfma_f32_16x16x32_bf16 v[80:83], v[150:153], v[198:201], v[80:83]
	v_mfma_f32_16x16x32_bf16 v[76:79], v[158:161], v[198:201], v[76:79]
	v_mfma_f32_16x16x32_bf16 v[128:131], v[154:157], v[170:173], v[128:131]
	v_mfma_f32_16x16x32_bf16 v[124:127], v[162:165], v[170:173], v[124:127]
	v_mfma_f32_16x16x32_bf16 v[112:115], v[154:157], v[186:189], v[112:115]
	v_mfma_f32_16x16x32_bf16 v[108:111], v[162:165], v[186:189], v[108:111]
	v_mfma_f32_16x16x32_bf16 v[96:99], v[154:157], v[194:197], v[96:99]
	v_mfma_f32_16x16x32_bf16 v[92:95], v[162:165], v[194:197], v[92:95]
	v_mfma_f32_16x16x32_bf16 v[80:83], v[154:157], v[202:205], v[80:83]
	v_mfma_f32_16x16x32_bf16 v[76:79], v[162:165], v[202:205], v[76:79]
	s_barrier
	s_add_i32 s3, 0, 0x1c000
	s_add_i32 s38, s79, s41
	v_lshl_add_u64 v[174:175], v[174:175], 0, s[16:17]
	s_mov_b32 m0, s38
	ds_read_b128 v[206:209], v253
	ds_read_b128 v[214:217], v253 offset:1024
	ds_read_b128 v[218:221], v253 offset:2048
	ds_read_b128 v[222:225], v253 offset:3072
	global_load_lds_dwordx4 v[174:175], off
	s_add_i32 m0, s38, 0x2000
	v_lshl_add_u64 v[174:175], v[226:227], 0, s[16:17]
	global_load_lds_dwordx4 v[174:175], off
	s_barrier
	s_waitcnt lgkmcnt(0)
	v_mfma_f32_16x16x32_bf16 v[120:123], v[206:209], v[166:169], v[120:123]
	v_mfma_f32_16x16x32_bf16 v[116:119], v[218:221], v[166:169], v[116:119]
	v_mfma_f32_16x16x32_bf16 v[104:107], v[206:209], v[182:185], v[104:107]
	v_mfma_f32_16x16x32_bf16 v[100:103], v[218:221], v[182:185], v[100:103]
	v_mfma_f32_16x16x32_bf16 v[88:91], v[206:209], v[190:193], v[88:91]
	v_mfma_f32_16x16x32_bf16 v[84:87], v[218:221], v[190:193], v[84:87]
	v_mfma_f32_16x16x32_bf16 v[72:75], v[206:209], v[198:201], v[72:75]
	v_mfma_f32_16x16x32_bf16 v[68:71], v[218:221], v[198:201], v[68:71]
	v_mfma_f32_16x16x32_bf16 v[120:123], v[214:217], v[170:173], v[120:123]
	v_mfma_f32_16x16x32_bf16 v[116:119], v[222:225], v[170:173], v[116:119]
	v_mfma_f32_16x16x32_bf16 v[104:107], v[214:217], v[186:189], v[104:107]
	v_mfma_f32_16x16x32_bf16 v[100:103], v[222:225], v[186:189], v[100:103]
	v_mfma_f32_16x16x32_bf16 v[88:91], v[214:217], v[194:197], v[88:91]
	v_mfma_f32_16x16x32_bf16 v[84:87], v[222:225], v[194:197], v[84:87]
	v_mfma_f32_16x16x32_bf16 v[72:75], v[214:217], v[202:205], v[72:75]
	v_mfma_f32_16x16x32_bf16 v[68:71], v[222:225], v[202:205], v[68:71]
	s_mov_b32 m0, s67
	v_lshl_add_u64 v[174:175], v[228:229], 0, s[16:17]
	s_barrier
	ds_read_b128 v[166:169], v133 offset:49152
	ds_read_b128 v[170:173], v133 offset:50176
	ds_read_b128 v[182:185], v133 offset:51200
	ds_read_b128 v[186:189], v133 offset:52224
	ds_read_b128 v[190:193], v133 offset:53248
	ds_read_b128 v[194:197], v133 offset:54272
	ds_read_b128 v[198:201], v133 offset:55296
	ds_read_b128 v[202:205], v133 offset:56320
	global_load_lds_dwordx4 v[174:175], off
	s_mov_b32 m0, s68
	v_lshl_add_u64 v[174:175], v[230:231], 0, s[16:17]
	global_load_lds_dwordx4 v[174:175], off
	s_barrier
	s_waitcnt lgkmcnt(0)
	v_mfma_f32_16x16x32_bf16 v[64:67], v[150:153], v[166:169], v[64:67]
	v_mfma_f32_16x16x32_bf16 v[60:63], v[158:161], v[166:169], v[60:63]
	v_mfma_f32_16x16x32_bf16 v[44:47], v[150:153], v[182:185], v[44:47]
	v_mfma_f32_16x16x32_bf16 v[40:43], v[158:161], v[182:185], v[40:43]
	v_mfma_f32_16x16x32_bf16 v[28:31], v[150:153], v[190:193], v[28:31]
	v_mfma_f32_16x16x32_bf16 v[24:27], v[158:161], v[190:193], v[24:27]
	v_mfma_f32_16x16x32_bf16 v[12:15], v[150:153], v[198:201], v[12:15]
	v_mfma_f32_16x16x32_bf16 v[8:11], v[158:161], v[198:201], v[8:11]
	v_mfma_f32_16x16x32_bf16 v[64:67], v[154:157], v[170:173], v[64:67]
	v_mfma_f32_16x16x32_bf16 v[60:63], v[162:165], v[170:173], v[60:63]
	v_mfma_f32_16x16x32_bf16 v[44:47], v[154:157], v[186:189], v[44:47]
	v_mfma_f32_16x16x32_bf16 v[40:43], v[162:165], v[186:189], v[40:43]
	v_mfma_f32_16x16x32_bf16 v[28:31], v[154:157], v[194:197], v[28:31]
	v_mfma_f32_16x16x32_bf16 v[24:27], v[162:165], v[194:197], v[24:27]
	v_mfma_f32_16x16x32_bf16 v[12:15], v[154:157], v[202:205], v[12:15]
	v_mfma_f32_16x16x32_bf16 v[8:11], v[162:165], v[202:205], v[8:11]
	s_barrier
	s_add_u32 s36, s36, 0x100080
	s_addc_u32 s37, s37, 0
	s_add_i32 s3, s3, s41
	s_mov_b32 m0, s3
	v_lshl_add_u64 v[150:151], s[36:37], 0, v[134:135]
	global_load_lds_dwordx4 v[150:151], off
	s_add_i32 m0, s3, 0x2000
	v_lshl_add_u64 v[150:151], s[36:37], 0, v[136:137]
	global_load_lds_dwordx4 v[150:151], off
	s_waitcnt vmcnt(6)
	s_barrier
	v_mfma_f32_16x16x32_bf16 v[52:55], v[206:209], v[166:169], v[52:55]
	v_mfma_f32_16x16x32_bf16 v[48:51], v[218:221], v[166:169], v[48:51]
	v_mfma_f32_16x16x32_bf16 v[36:39], v[206:209], v[182:185], v[36:39]
	v_mfma_f32_16x16x32_bf16 v[32:35], v[218:221], v[182:185], v[32:35]
	v_mfma_f32_16x16x32_bf16 v[20:23], v[206:209], v[190:193], v[20:23]
	v_mfma_f32_16x16x32_bf16 v[16:19], v[218:221], v[190:193], v[16:19]
	v_mfma_f32_16x16x32_bf16 v[4:7], v[206:209], v[198:201], v[4:7]
	v_mfma_f32_16x16x32_bf16 v[0:3], v[218:221], v[198:201], v[0:3]
	v_mfma_f32_16x16x32_bf16 v[52:55], v[214:217], v[170:173], v[52:55]
	v_mfma_f32_16x16x32_bf16 v[48:51], v[222:225], v[170:173], v[48:51]
	v_mfma_f32_16x16x32_bf16 v[36:39], v[214:217], v[186:189], v[36:39]
	v_mfma_f32_16x16x32_bf16 v[32:35], v[222:225], v[186:189], v[32:35]
	v_mfma_f32_16x16x32_bf16 v[20:23], v[214:217], v[194:197], v[20:23]
	v_mfma_f32_16x16x32_bf16 v[16:19], v[222:225], v[194:197], v[16:19]
	v_mfma_f32_16x16x32_bf16 v[4:7], v[214:217], v[202:205], v[4:7]
	v_mfma_f32_16x16x32_bf16 v[0:3], v[222:225], v[202:205], v[0:3]
	s_add_u32 s34, s34, 0x100
	s_addc_u32 s35, s35, 0
	s_cmp_ge_u32 s89, s49
	s_barrier
	s_cbranch_scc1 .Lpeel_done_out
.LBB0_640:
	s_add_i32 s89, s89, 2
	s_add_u32 s3, s22, s34
	ds_read_b128 v[150:153], v250
	ds_read_b128 v[154:157], v250 offset:1024
	ds_read_b128 v[158:161], v250 offset:2048
	ds_read_b128 v[162:165], v250 offset:3072
	s_addc_u32 s36, s23, s35
	s_add_u32 s3, s3, 0x100
	s_addc_u32 s36, s36, 0
	s_add_u32 s90, s83, s34
	s_addc_u32 s37, s84, s35
	s_cmp_eq_u32 s88, s34
	s_cselect_b32 s39, s11, s36
	s_cselect_b32 s38, s85, s3
	s_cselect_b32 s37, s86, s37
	s_cselect_b32 s36, s87, s90
	s_mov_b32 m0, s73
	v_lshl_add_u64 v[174:175], v[58:59], 0, s[34:35]
	ds_read_b128 v[166:169], v133
	ds_read_b128 v[170:173], v133 offset:1024
	ds_read_b128 v[182:185], v133 offset:2048
	ds_read_b128 v[186:189], v133 offset:3072
	ds_read_b128 v[190:193], v133 offset:4096
	ds_read_b128 v[194:197], v133 offset:5120
	ds_read_b128 v[198:201], v133 offset:6144
	ds_read_b128 v[202:205], v133 offset:7168
	global_load_lds_dwordx4 v[174:175], off
	s_mov_b32 m0, s74
	v_lshl_add_u64 v[174:175], v[146:147], 0, s[34:35]
	global_load_lds_dwordx4 v[174:175], off
	s_waitcnt lgkmcnt(8)
	s_barrier
	s_waitcnt lgkmcnt(0)
	v_mfma_f32_16x16x32_bf16 v[128:131], v[150:153], v[166:169], v[128:131]
	v_mfma_f32_16x16x32_bf16 v[124:127], v[158:161], v[166:169], v[124:127]
	v_mfma_f32_16x16x32_bf16 v[112:115], v[150:153], v[182:185], v[112:115]
	v_mfma_f32_16x16x32_bf16 v[108:111], v[158:161], v[182:185], v[108:111]
	v_mfma_f32_16x16x32_bf16 v[96:99], v[150:153], v[190:193], v[96:99]
	v_mfma_f32_16x16x32_bf16 v[92:95], v[158:161], v[190:193], v[92:95]
	v_mfma_f32_16x16x32_bf16 v[80:83], v[150:153], v[198:201], v[80:83]
	v_mfma_f32_16x16x32_bf16 v[76:79], v[158:161], v[198:201], v[76:79]
	v_mfma_f32_16x16x32_bf16 v[128:131], v[154:157], v[170:173], v[128:131]
	v_mfma_f32_16x16x32_bf16 v[124:127], v[162:165], v[170:173], v[124:127]
	v_mfma_f32_16x16x32_bf16 v[112:115], v[154:157], v[186:189], v[112:115]
	v_mfma_f32_16x16x32_bf16 v[108:111], v[162:165], v[186:189], v[108:111]
	v_mfma_f32_16x16x32_bf16 v[96:99], v[154:157], v[194:197], v[96:99]
	v_mfma_f32_16x16x32_bf16 v[92:95], v[162:165], v[194:197], v[92:95]
	v_mfma_f32_16x16x32_bf16 v[80:83], v[154:157], v[202:205], v[80:83]
	v_mfma_f32_16x16x32_bf16 v[76:79], v[162:165], v[202:205], v[76:79]
	s_barrier
	s_mov_b32 m0, s75
	v_lshl_add_u64 v[174:175], s[36:37], 0, v[134:135]
	ds_read_b128 v[206:209], v251
	ds_read_b128 v[214:217], v251 offset:1024
	ds_read_b128 v[218:221], v251 offset:2048
	ds_read_b128 v[222:225], v251 offset:3072
	global_load_lds_dwordx4 v[174:175], off
	s_mov_b32 m0, s76
	v_lshl_add_u64 v[226:227], s[36:37], 0, v[136:137]
	global_load_lds_dwordx4 v[226:227], off
	s_barrier
	s_waitcnt lgkmcnt(0)
	v_mfma_f32_16x16x32_bf16 v[120:123], v[206:209], v[166:169], v[120:123]
	v_mfma_f32_16x16x32_bf16 v[116:119], v[218:221], v[166:169], v[116:119]
	v_mfma_f32_16x16x32_bf16 v[104:107], v[206:209], v[182:185], v[104:107]
	v_mfma_f32_16x16x32_bf16 v[100:103], v[218:221], v[182:185], v[100:103]
	v_mfma_f32_16x16x32_bf16 v[88:91], v[206:209], v[190:193], v[88:91]
	v_mfma_f32_16x16x32_bf16 v[84:87], v[218:221], v[190:193], v[84:87]
	v_mfma_f32_16x16x32_bf16 v[72:75], v[206:209], v[198:201], v[72:75]
	v_mfma_f32_16x16x32_bf16 v[68:71], v[218:221], v[198:201], v[68:71]
	v_mfma_f32_16x16x32_bf16 v[120:123], v[214:217], v[170:173], v[120:123]
	v_mfma_f32_16x16x32_bf16 v[116:119], v[222:225], v[170:173], v[116:119]
	v_mfma_f32_16x16x32_bf16 v[104:107], v[214:217], v[186:189], v[104:107]
	v_mfma_f32_16x16x32_bf16 v[100:103], v[222:225], v[186:189], v[100:103]
	v_mfma_f32_16x16x32_bf16 v[88:91], v[214:217], v[194:197], v[88:91]
	v_mfma_f32_16x16x32_bf16 v[84:87], v[222:225], v[194:197], v[84:87]
	v_mfma_f32_16x16x32_bf16 v[72:75], v[214:217], v[202:205], v[72:75]
	v_mfma_f32_16x16x32_bf16 v[68:71], v[222:225], v[202:205], v[68:71]
	s_mov_b32 m0, s44
	v_lshl_add_u64 v[228:229], s[38:39], 0, v[134:135]
	s_barrier
	ds_read_b128 v[166:169], v133 offset:16384
	ds_read_b128 v[170:173], v133 offset:17408
	ds_read_b128 v[182:185], v133 offset:18432
	ds_read_b128 v[186:189], v133 offset:19456
	ds_read_b128 v[190:193], v133 offset:20480
	ds_read_b128 v[194:197], v133 offset:21504
	ds_read_b128 v[198:201], v133 offset:22528
	ds_read_b128 v[202:205], v133 offset:23552
	global_load_lds_dwordx4 v[228:229], off
	s_mov_b32 m0, s45
	v_lshl_add_u64 v[230:231], s[38:39], 0, v[136:137]
	global_load_lds_dwordx4 v[230:231], off
	s_barrier
	s_waitcnt lgkmcnt(0)
	v_mfma_f32_16x16x32_bf16 v[64:67], v[150:153], v[166:169], v[64:67]
	v_mfma_f32_16x16x32_bf16 v[60:63], v[158:161], v[166:169], v[60:63]
	v_mfma_f32_16x16x32_bf16 v[44:47], v[150:153], v[182:185], v[44:47]
	v_mfma_f32_16x16x32_bf16 v[40:43], v[158:161], v[182:185], v[40:43]
	v_mfma_f32_16x16x32_bf16 v[28:31], v[150:153], v[190:193], v[28:31]
	v_mfma_f32_16x16x32_bf16 v[24:27], v[158:161], v[190:193], v[24:27]
	v_mfma_f32_16x16x32_bf16 v[12:15], v[150:153], v[198:201], v[12:15]
	v_mfma_f32_16x16x32_bf16 v[8:11], v[158:161], v[198:201], v[8:11]
	v_mfma_f32_16x16x32_bf16 v[64:67], v[154:157], v[170:173], v[64:67]
	v_mfma_f32_16x16x32_bf16 v[60:63], v[162:165], v[170:173], v[60:63]
	v_mfma_f32_16x16x32_bf16 v[44:47], v[154:157], v[186:189], v[44:47]
	v_mfma_f32_16x16x32_bf16 v[40:43], v[162:165], v[186:189], v[40:43]
	v_mfma_f32_16x16x32_bf16 v[28:31], v[154:157], v[194:197], v[28:31]
	v_mfma_f32_16x16x32_bf16 v[24:27], v[162:165], v[194:197], v[24:27]
	v_mfma_f32_16x16x32_bf16 v[12:15], v[154:157], v[202:205], v[12:15]
	v_mfma_f32_16x16x32_bf16 v[8:11], v[162:165], v[202:205], v[8:11]
	s_barrier
	s_add_u32 s90, s36, 0x100000
	s_addc_u32 s91, s37, 0
	s_mov_b32 m0, s77
	v_lshl_add_u64 v[150:151], s[90:91], 0, v[134:135]
	global_load_lds_dwordx4 v[150:151], off
	s_mov_b32 m0, s78
	v_lshl_add_u64 v[150:151], s[90:91], 0, v[136:137]
	global_load_lds_dwordx4 v[150:151], off
	s_waitcnt vmcnt(6)
	s_barrier
	v_mfma_f32_16x16x32_bf16 v[52:55], v[206:209], v[166:169], v[52:55]
	v_mfma_f32_16x16x32_bf16 v[48:51], v[218:221], v[166:169], v[48:51]
	v_mfma_f32_16x16x32_bf16 v[36:39], v[206:209], v[182:185], v[36:39]
	v_mfma_f32_16x16x32_bf16 v[32:35], v[218:221], v[182:185], v[32:35]
	v_mfma_f32_16x16x32_bf16 v[20:23], v[206:209], v[190:193], v[20:23]
	v_mfma_f32_16x16x32_bf16 v[16:19], v[218:221], v[190:193], v[16:19]
	v_mfma_f32_16x16x32_bf16 v[4:7], v[206:209], v[198:201], v[4:7]
	v_mfma_f32_16x16x32_bf16 v[0:3], v[218:221], v[198:201], v[0:3]
	v_mfma_f32_16x16x32_bf16 v[52:55], v[214:217], v[170:173], v[52:55]
	v_mfma_f32_16x16x32_bf16 v[48:51], v[222:225], v[170:173], v[48:51]
	v_mfma_f32_16x16x32_bf16 v[36:39], v[214:217], v[186:189], v[36:39]
	v_mfma_f32_16x16x32_bf16 v[32:35], v[222:225], v[186:189], v[32:35]
	v_mfma_f32_16x16x32_bf16 v[20:23], v[214:217], v[194:197], v[20:23]
	v_mfma_f32_16x16x32_bf16 v[16:19], v[222:225], v[194:197], v[16:19]
	v_mfma_f32_16x16x32_bf16 v[4:7], v[214:217], v[202:205], v[4:7]
	v_mfma_f32_16x16x32_bf16 v[0:3], v[222:225], v[202:205], v[0:3]
	s_barrier
	ds_read_b128 v[150:153], v252
	ds_read_b128 v[154:157], v252 offset:1024
	ds_read_b128 v[158:161], v252 offset:2048
	ds_read_b128 v[162:165], v252 offset:3072
	s_add_u32 s38, s38, 0x100000
	s_addc_u32 s39, s39, 0
	s_mov_b32 m0, s46
	v_lshl_add_u64 v[206:207], s[38:39], 0, v[134:135]
	ds_read_b128 v[166:169], v133 offset:32768
	ds_read_b128 v[170:173], v133 offset:33792
	ds_read_b128 v[182:185], v133 offset:34816
	ds_read_b128 v[186:189], v133 offset:35840
	ds_read_b128 v[190:193], v133 offset:36864
	ds_read_b128 v[194:197], v133 offset:37888
	ds_read_b128 v[198:201], v133 offset:38912
	ds_read_b128 v[202:205], v133 offset:39936
	global_load_lds_dwordx4 v[206:207], off
	s_mov_b32 m0, s47
	v_lshl_add_u64 v[206:207], s[38:39], 0, v[136:137]
	global_load_lds_dwordx4 v[206:207], off
	s_waitcnt lgkmcnt(8)
	s_barrier
	s_waitcnt lgkmcnt(0)
	v_mfma_f32_16x16x32_bf16 v[128:131], v[150:153], v[166:169], v[128:131]
	v_mfma_f32_16x16x32_bf16 v[124:127], v[158:161], v[166:169], v[124:127]
	v_mfma_f32_16x16x32_bf16 v[112:115], v[150:153], v[182:185], v[112:115]
	v_mfma_f32_16x16x32_bf16 v[108:111], v[158:161], v[182:185], v[108:111]
	v_mfma_f32_16x16x32_bf16 v[96:99], v[150:153], v[190:193], v[96:99]
	v_mfma_f32_16x16x32_bf16 v[92:95], v[158:161], v[190:193], v[92:95]
	v_mfma_f32_16x16x32_bf16 v[80:83], v[150:153], v[198:201], v[80:83]
	v_mfma_f32_16x16x32_bf16 v[76:79], v[158:161], v[198:201], v[76:79]
	v_mfma_f32_16x16x32_bf16 v[128:131], v[154:157], v[170:173], v[128:131]
	v_mfma_f32_16x16x32_bf16 v[124:127], v[162:165], v[170:173], v[124:127]
	v_mfma_f32_16x16x32_bf16 v[112:115], v[154:157], v[186:189], v[112:115]
	v_mfma_f32_16x16x32_bf16 v[108:111], v[162:165], v[186:189], v[108:111]
	v_mfma_f32_16x16x32_bf16 v[96:99], v[154:157], v[194:197], v[96:99]
	v_mfma_f32_16x16x32_bf16 v[92:95], v[162:165], v[194:197], v[92:95]
	v_mfma_f32_16x16x32_bf16 v[80:83], v[154:157], v[202:205], v[80:83]
	v_mfma_f32_16x16x32_bf16 v[76:79], v[162:165], v[202:205], v[76:79]
	s_barrier
	s_add_i32 s3, 0, 0x1c000
	s_add_i32 s38, s79, s41
	v_lshl_add_u64 v[174:175], v[174:175], 0, s[16:17]
	s_mov_b32 m0, s38
	ds_read_b128 v[206:209], v253
	ds_read_b128 v[214:217], v253 offset:1024
	ds_read_b128 v[218:221], v253 offset:2048
	ds_read_b128 v[222:225], v253 offset:3072
	global_load_lds_dwordx4 v[174:175], off
	s_add_i32 m0, s38, 0x2000
	v_lshl_add_u64 v[174:175], v[226:227], 0, s[16:17]
	global_load_lds_dwordx4 v[174:175], off
	s_barrier
	s_waitcnt lgkmcnt(0)
	v_mfma_f32_16x16x32_bf16 v[120:123], v[206:209], v[166:169], v[120:123]
	v_mfma_f32_16x16x32_bf16 v[116:119], v[218:221], v[166:169], v[116:119]
	v_mfma_f32_16x16x32_bf16 v[104:107], v[206:209], v[182:185], v[104:107]
	v_mfma_f32_16x16x32_bf16 v[100:103], v[218:221], v[182:185], v[100:103]
	v_mfma_f32_16x16x32_bf16 v[88:91], v[206:209], v[190:193], v[88:91]
	v_mfma_f32_16x16x32_bf16 v[84:87], v[218:221], v[190:193], v[84:87]
	v_mfma_f32_16x16x32_bf16 v[72:75], v[206:209], v[198:201], v[72:75]
	v_mfma_f32_16x16x32_bf16 v[68:71], v[218:221], v[198:201], v[68:71]
	v_mfma_f32_16x16x32_bf16 v[120:123], v[214:217], v[170:173], v[120:123]
	v_mfma_f32_16x16x32_bf16 v[116:119], v[222:225], v[170:173], v[116:119]
	v_mfma_f32_16x16x32_bf16 v[104:107], v[214:217], v[186:189], v[104:107]
	v_mfma_f32_16x16x32_bf16 v[100:103], v[222:225], v[186:189], v[100:103]
	v_mfma_f32_16x16x32_bf16 v[88:91], v[214:217], v[194:197], v[88:91]
	v_mfma_f32_16x16x32_bf16 v[84:87], v[222:225], v[194:197], v[84:87]
	v_mfma_f32_16x16x32_bf16 v[72:75], v[214:217], v[202:205], v[72:75]
	v_mfma_f32_16x16x32_bf16 v[68:71], v[222:225], v[202:205], v[68:71]
	s_mov_b32 m0, s67
	v_lshl_add_u64 v[174:175], v[228:229], 0, s[16:17]
	s_barrier
	ds_read_b128 v[166:169], v133 offset:49152
	ds_read_b128 v[170:173], v133 offset:50176
	ds_read_b128 v[182:185], v133 offset:51200
	ds_read_b128 v[186:189], v133 offset:52224
	ds_read_b128 v[190:193], v133 offset:53248
	ds_read_b128 v[194:197], v133 offset:54272
	ds_read_b128 v[198:201], v133 offset:55296
	ds_read_b128 v[202:205], v133 offset:56320
	global_load_lds_dwordx4 v[174:175], off
	s_mov_b32 m0, s68
	v_lshl_add_u64 v[174:175], v[230:231], 0, s[16:17]
	global_load_lds_dwordx4 v[174:175], off
	s_barrier
	s_waitcnt lgkmcnt(0)
	v_mfma_f32_16x16x32_bf16 v[64:67], v[150:153], v[166:169], v[64:67]
	v_mfma_f32_16x16x32_bf16 v[60:63], v[158:161], v[166:169], v[60:63]
	v_mfma_f32_16x16x32_bf16 v[44:47], v[150:153], v[182:185], v[44:47]
	v_mfma_f32_16x16x32_bf16 v[40:43], v[158:161], v[182:185], v[40:43]
	v_mfma_f32_16x16x32_bf16 v[28:31], v[150:153], v[190:193], v[28:31]
	v_mfma_f32_16x16x32_bf16 v[24:27], v[158:161], v[190:193], v[24:27]
	v_mfma_f32_16x16x32_bf16 v[12:15], v[150:153], v[198:201], v[12:15]
	v_mfma_f32_16x16x32_bf16 v[8:11], v[158:161], v[198:201], v[8:11]
	v_mfma_f32_16x16x32_bf16 v[64:67], v[154:157], v[170:173], v[64:67]
	v_mfma_f32_16x16x32_bf16 v[60:63], v[162:165], v[170:173], v[60:63]
	v_mfma_f32_16x16x32_bf16 v[44:47], v[154:157], v[186:189], v[44:47]
	v_mfma_f32_16x16x32_bf16 v[40:43], v[162:165], v[186:189], v[40:43]
	v_mfma_f32_16x16x32_bf16 v[28:31], v[154:157], v[194:197], v[28:31]
	v_mfma_f32_16x16x32_bf16 v[24:27], v[162:165], v[194:197], v[24:27]
	v_mfma_f32_16x16x32_bf16 v[12:15], v[154:157], v[202:205], v[12:15]
	v_mfma_f32_16x16x32_bf16 v[8:11], v[162:165], v[202:205], v[8:11]
	s_barrier
	s_add_u32 s36, s36, 0x100080
	s_addc_u32 s37, s37, 0
	s_add_i32 s3, s3, s41
	s_mov_b32 m0, s3
	v_lshl_add_u64 v[150:151], s[36:37], 0, v[134:135]
	global_load_lds_dwordx4 v[150:151], off
	s_add_i32 m0, s3, 0x2000
	v_lshl_add_u64 v[150:151], s[36:37], 0, v[136:137]
	global_load_lds_dwordx4 v[150:151], off
	s_waitcnt vmcnt(6)
	s_barrier
	v_mfma_f32_16x16x32_bf16 v[52:55], v[206:209], v[166:169], v[52:55]
	v_mfma_f32_16x16x32_bf16 v[48:51], v[218:221], v[166:169], v[48:51]
	v_mfma_f32_16x16x32_bf16 v[36:39], v[206:209], v[182:185], v[36:39]
	v_mfma_f32_16x16x32_bf16 v[32:35], v[218:221], v[182:185], v[32:35]
	v_mfma_f32_16x16x32_bf16 v[20:23], v[206:209], v[190:193], v[20:23]
	v_mfma_f32_16x16x32_bf16 v[16:19], v[218:221], v[190:193], v[16:19]
	v_mfma_f32_16x16x32_bf16 v[4:7], v[206:209], v[198:201], v[4:7]
	v_mfma_f32_16x16x32_bf16 v[0:3], v[218:221], v[198:201], v[0:3]
	v_mfma_f32_16x16x32_bf16 v[52:55], v[214:217], v[170:173], v[52:55]
	v_mfma_f32_16x16x32_bf16 v[48:51], v[222:225], v[170:173], v[48:51]
	v_mfma_f32_16x16x32_bf16 v[36:39], v[214:217], v[186:189], v[36:39]
	v_mfma_f32_16x16x32_bf16 v[32:35], v[222:225], v[186:189], v[32:35]
	v_mfma_f32_16x16x32_bf16 v[20:23], v[214:217], v[194:197], v[20:23]
	v_mfma_f32_16x16x32_bf16 v[16:19], v[222:225], v[194:197], v[16:19]
	v_mfma_f32_16x16x32_bf16 v[4:7], v[214:217], v[202:205], v[4:7]
	v_mfma_f32_16x16x32_bf16 v[0:3], v[222:225], v[202:205], v[0:3]
	s_add_u32 s34, s34, 0x100
	s_addc_u32 s35, s35, 0
	s_cmp_ge_u32 s89, s49
	s_barrier
	s_cbranch_scc0 .LBB0_640
